# v65 plus odd workgroups run the s=3 wave units (sc/foxprep streaming) before their block units, even ones after: streaming overlaps compute across workgroups
# baseline (speedup 1.0000x reference)
.LBB0_18:
	s_load_dwordx2 s[2:3], s[0:1], 0xf0
	s_add_u32 s4, s74, 0x4000000
	s_addc_u32 s5, s75, 0
	s_add_u32 s30, s74, 0x5000000
	s_addc_u32 s31, s75, 0
	s_waitcnt lgkmcnt(0)
	s_mul_i32 s2, s3, s2
	s_load_dword s3, s[0:1], 0xf8
	v_writelane_b32 v254, s4, 3
	s_cmp_eq_u64 s[74:75], 0
	v_mov_b32_e32 v1, 0
	v_writelane_b32 v254, s5, 4
	s_cselect_b64 s[4:5], -1, 0
	v_writelane_b32 v254, s4, 5
	s_waitcnt lgkmcnt(0)
	s_mul_i32 s26, s2, s3
	s_add_u32 s2, s22, 0x1000
	v_writelane_b32 v254, s5, 6
	s_addc_u32 s3, s23, 0
	v_writelane_b32 v254, s2, 7
	v_mbcnt_lo_u32_b32 v0, -1, 0
	s_mov_b32 s29, 0x40000
	v_writelane_b32 v254, s3, 8
	s_add_u32 s2, s22, 0x1100
	s_addc_u32 s3, s23, 0
	v_writelane_b32 v254, s2, 9
	v_mov_b32_e32 v172, 0x3ecc95a3
	v_mov_b32_e32 v173, 0x358637bd
	v_writelane_b32 v254, s3, 10
	s_add_u32 s2, s22, 0x1200
	s_addc_u32 s3, s23, 0
	v_writelane_b32 v254, s2, 11
	v_mov_b32_e32 v145, 0xc2400000
	v_mbcnt_hi_u32_b32 v174, -1, v0
	v_writelane_b32 v254, s3, 12
	s_add_u32 s2, s22, 0x1300
	s_addc_u32 s3, s23, 0
	v_writelane_b32 v254, s2, 13
	s_cmp_eq_u32 s10, 15
	v_mov_b32_e32 v175, 0x7f800000
	v_writelane_b32 v254, s3, 14
	s_cselect_b64 s[2:3], -1, 0
	v_writelane_b32 v254, s2, 15
	s_cmp_eq_u32 s10, 14
	v_mov_b32_e32 v176, 0x7fc00000
	v_writelane_b32 v254, s3, 16
	s_cselect_b64 s[2:3], -1, 0
	v_writelane_b32 v254, s2, 17
	s_cmp_eq_u32 s10, 13
	v_mov_b32_e32 v177, 0xff800000
	v_writelane_b32 v254, s3, 18
	s_cselect_b64 s[2:3], -1, 0
	v_writelane_b32 v254, s2, 19
	s_cmp_eq_u32 s10, 12
	v_mov_b32_e32 v178, 0x9fc
	v_writelane_b32 v254, s3, 20
	s_cselect_b64 s[2:3], -1, 0
	v_writelane_b32 v254, s2, 21
	s_cmp_eq_u32 s10, 11
	v_mov_b32_e32 v179, 0x41b17218
	v_writelane_b32 v254, s3, 22
	s_cselect_b64 s[2:3], -1, 0
	v_writelane_b32 v254, s2, 23
	s_cmp_eq_u32 s10, 10
	v_mov_b32_e32 v146, 0x3f317218
	v_writelane_b32 v254, s3, 24
	s_cselect_b64 s[2:3], -1, 0
	v_writelane_b32 v254, s2, 25
	s_cmp_eq_u32 s10, 9
	v_mov_b32_e32 v180, 1
	v_writelane_b32 v254, s3, 26
	s_cselect_b64 s[2:3], -1, 0
	v_writelane_b32 v254, s2, 27
	s_cmp_eq_u32 s10, 8
	v_mov_b32_e32 v220, v1
	v_writelane_b32 v254, s3, 28
	s_cselect_b64 s[2:3], -1, 0
	v_writelane_b32 v254, s2, 29
	s_cmp_eq_u32 s10, 7
	v_mov_b32_e32 v221, v1
	v_writelane_b32 v254, s3, 30
	s_cselect_b64 s[2:3], -1, 0
	v_writelane_b32 v254, s2, 31
	s_cmp_eq_u32 s10, 6
	v_mov_b32_e32 v222, v1
	v_writelane_b32 v254, s3, 32
	s_cselect_b64 s[2:3], -1, 0
	v_writelane_b32 v254, s2, 33
	s_cmp_eq_u32 s10, 5
	v_mov_b32_e32 v223, v1
	v_writelane_b32 v254, s3, 34
	s_cselect_b64 s[2:3], -1, 0
	v_writelane_b32 v254, s2, 35
	s_cmp_eq_u32 s10, 4
	v_mov_b32_e32 v181, 0
	v_writelane_b32 v254, s3, 36
	s_cselect_b64 s[2:3], -1, 0
	v_writelane_b32 v254, s2, 37
	s_cmp_eq_u32 s10, 3
	s_movk_i32 s18, 0x1e00
	v_writelane_b32 v254, s3, 38
	s_cselect_b64 s[2:3], -1, 0
	v_writelane_b32 v254, s2, 39
	s_cmp_eq_u32 s10, 2
	s_mov_b32 s19, 0xbfb8aa3b
	v_writelane_b32 v254, s3, 40
	s_cselect_b64 s[2:3], -1, 0
	v_writelane_b32 v254, s2, 41
	s_cmp_eq_u32 s10, 1
	s_mov_b32 s86, 0x3f2aaaab
	v_writelane_b32 v254, s3, 42
	s_cselect_b64 s[2:3], -1, 0
	v_writelane_b32 v254, s2, 43
	s_cmp_eq_u32 s10, 0
	s_mov_b32 s87, 0x3f317218
	v_writelane_b32 v254, s3, 44
	s_cselect_b64 s[2:3], -1, 0
	v_writelane_b32 v254, s2, 45
	s_mov_b32 s15, 0x7f800000
	s_mov_b32 s88, 0x33800000
	v_writelane_b32 v254, s3, 46
	s_lshl_b32 s2, s10, 8
	s_add_u32 s2, s22, s2
	s_addc_u32 s3, s23, 0
	s_add_u32 s2, s2, 0x1400
	s_addc_u32 s3, s3, 0
	v_writelane_b32 v254, s2, 47
	s_mov_b32 s96, 0x800000
	s_mov_b32 s97, 0x3f317217
	v_writelane_b32 v254, s3, 48
	s_add_u32 s2, s22, 0x3400
	s_addc_u32 s3, s23, 0
	v_writelane_b32 v254, s2, 49
	s_movk_i32 s89, 0x90
	s_mov_b32 s33, 0xffff0000
	v_writelane_b32 v254, s3, 50
	s_add_u32 s2, s22, 0x3500
	s_addc_u32 s3, s23, 0
	v_writelane_b32 v254, s2, 51
	s_mov_b32 s17, 0x5040100
	s_movk_i32 s14, 0x1600
	v_writelane_b32 v254, s3, 52
	s_add_i32 s2, 0, 0x8800
	v_writelane_b32 v254, s2, 53
	s_add_i32 s2, 0, 0x11000
	v_writelane_b32 v254, s2, 54
	s_add_i32 s2, 0, 0x19800
	v_writelane_b32 v254, s2, 55
	s_add_i32 s2, 0, 0x8400
	v_writelane_b32 v254, s2, 56
	s_add_i32 s2, 0, 0x10800
	v_writelane_b32 v254, s2, 57
	s_add_i32 s2, 0, 0x1a800
	v_writelane_b32 v254, s2, 58
	s_add_i32 s2, 0, 0x257c0
	v_writelane_b32 v254, s2, 59
	s_add_i32 s2, 0, 0x257c4
	v_writelane_b32 v254, s2, 60
	v_writelane_b32 v254, s26, 61
	v_writelane_b32 v254, s30, 62
	s_mov_b64 s[2:3], 0
	s_mov_b32 s81, 0
	s_mov_b64 s[8:9], 0xf000
	s_mov_b64 s[12:13], 0x80
	v_writelane_b32 v254, s31, 63
	s_nop 3
	v_writelane_b32 v255, s2, 42
	s_branch .LBB0_22

.LBB0_67:
	v_readlane_b32 s2, v255, 42
	s_nop 3
	s_cmp_lg_u32 s2, 0
	s_cbranch_scc1 .Lsw3_go
	v_readlane_b32 s3, v255, 16
	s_nop 3
	s_bitcmp1_b32 s3, 0
	s_cbranch_scc0 .Lsw3_go
	s_mov_b32 s2, 1
	s_nop 3
	v_writelane_b32 v255, s2, 42
	v_writelane_b32 v255, s30, 43
	v_writelane_b32 v255, s31, 44
	v_writelane_b32 v255, s50, 41
	s_nop 1
	s_branch .LBB0_112

.LBB0_115:
	v_readlane_b32 s2, v255, 42
	s_nop 3
	s_cmp_eq_u32 s2, 2
	s_cbranch_scc1 .LBB0_114
	s_cmpk_gt_i32 s4, 0x3ff
	s_mov_b64 s[2:3], -1
	s_cbranch_scc0 .LBB0_121
	s_mov_b32 s2, 10
	s_bfe_u32 s37, s4, 0x20008
	s_ashr_i32 s3, s2, 31
	s_bfe_u32 s50, s6, 0x80005
	s_lshl_b32 s51, s37, 22
	s_lshl_b64 s[2:3], s[2:3], 3
	s_add_u32 s2, s0, s2
	s_addc_u32 s3, s1, s3
	s_load_dwordx2 s[2:3], s[2:3], 0x0
	v_mov_b32_e32 v3, v183
	s_mov_b32 s21, s81
	v_and_b32_e32 v4, 63, v3
	s_waitcnt lgkmcnt(0)
	s_add_u32 s2, s2, s44
	v_lshlrev_b32_e32 v12, 16, v3
	v_bfe_u32 v5, v3, 2, 4
	v_and_b32_e32 v2, 3, v3
	v_and_b32_e32 v3, 60, v3
	s_addc_u32 s3, s3, s45
	v_lshlrev_b32_e32 v0, 2, v2
	v_lshl_or_b32 v3, s37, 17, v3
	v_cmp_gt_u32_e64 s[38:39], 32, v4
	v_lshl_add_u64 v[6:7], s[2:3], 0, v[0:1]
	v_lshlrev_b32_e32 v0, 3, v4
	v_add_u32_e32 v4, s7, v5
	v_lshl_or_b32 v3, v2, 15, v3
	v_and_b32_e32 v13, 0xf0000, v12
	v_mul_lo_u32 v25, v4, s18
	v_lshl_or_b32 v4, s50, 7, v3
	v_and_b32_e32 v3, 0x300000, v12
	s_mov_b32 s31, s81
	s_mov_b32 s35, s81
	s_mov_b32 s41, s81
	s_mov_b32 s43, s81
	v_lshl_add_u64 v[8:9], s[26:27], 0, v[0:1]
	v_mov_b32_e32 v5, v1
	s_mov_b64 s[2:3], 0x1d710000
	v_or3_b32 v3, s51, v3, v13
	v_or_b32_e32 v0, 0x9600c00, v0
	v_lshl_add_u64 v[10:11], v[4:5], 0, s[2:3]
	v_lshl_or_b32 v12, s50, 6, v3
	v_mov_b32_e32 v13, v1
	s_mov_b32 s2, 0
	v_lshl_add_u64 v[14:15], s[20:21], 1, v[0:1]
	v_lshl_add_u64 v[16:17], s[30:31], 1, v[0:1]
	v_lshl_add_u64 v[18:19], s[34:35], 1, v[0:1]
	v_lshl_add_u64 v[20:21], s[40:41], 1, v[0:1]
	v_lshl_add_u64 v[22:23], s[42:43], 1, v[0:1]
	v_lshlrev_b32_e32 v24, 1, v2
	v_mov_b32_e32 v0, v25
	global_load_dword v55, v[6:7], off
	s_branch .LBB0_118

.LBB0_127:
	v_readlane_b32 s2, v255, 42
	s_nop 3
	s_cmp_eq_u32 s2, 0
	s_cbranch_scc1 .Lsw3_end
	s_cmp_eq_u32 s2, 1
	s_cselect_b32 s2, 2, 0
	s_nop 3
	v_writelane_b32 v255, s2, 42
	s_cbranch_scc0 .Lsw3_end
	s_nop 1
	v_readlane_b32 s30, v255, 43
	v_readlane_b32 s31, v255, 44
	v_readlane_b32 s50, v255, 41
	s_nop 3
	s_branch .LBB0_67
